# LN1 and LN2 wave sums: the xor-1,2,4,8 butterfly stages use DPP adds instead of ds_bpermute round trips (xor-16 and xor-32 stay on ds_bpermute)
# speedup vs baseline: 1.0062x; 1.0062x over previous
.LBB0_1578:
	s_or_b64 exec, exec, s[24:25]
	v_pk_add_f32 v[10:11], v[108:109], v[24:25]
	v_pk_add_f32 v[22:23], v[106:107], v[26:27]
	s_waitcnt vmcnt(2)
	v_add_f32_e32 v13, v16, v17
	v_pk_add_f32 v[10:11], v[10:11], v[22:23]
	v_add_f32_e32 v105, v18, v19
	v_add_f32_e32 v11, 0, v11
	v_add_f32_e32 v103, v10, v11
	v_pk_add_f32 v[10:11], v[110:111], v[20:21]
	v_pk_add_f32 v[22:23], v[12:13], v[104:105]
	v_pk_add_f32 v[10:11], v[10:11], v[10:11] op_sel_hi:[0,1]
	v_mov_b32_e32 v15, v11
	v_pk_add_f32 v[10:11], v[14:15], v[102:103]
	s_waitcnt vmcnt(1)
	v_add_f32_e32 v29, v4, v5
	v_pk_add_f32 v[10:11], v[22:23], v[10:11]
	v_pk_add_f32 v[22:23], v[100:101], v[8:9]
	v_pk_add_f32 v[10:11], v[10:11], v[10:11] op_sel_hi:[0,1]
	v_pk_add_f32 v[22:23], v[22:23], v[22:23] op_sel_hi:[0,1]
	v_add_f32_e32 v31, v6, v7
	s_waitcnt vmcnt(0)
	v_mov_b32_e32 v28, v0
	v_mov_b32_e32 v30, v1
	v_mov_b32_e32 v22, v2
	v_mov_b32_e32 v10, v3
	v_pk_add_f32 v[28:29], v[28:29], v[30:31]
	v_pk_add_f32 v[10:11], v[22:23], v[10:11]
	v_xor_b32_e32 v13, 1, v39
	v_pk_add_f32 v[10:11], v[28:29], v[10:11]
	s_nop 0
	v_add_f32_e32 v10, v10, v11
	v_and_b32_e32 v11, 64, v39
	v_add_u32_e32 v11, 64, v11
	v_cmp_lt_i32_e32 vcc, v13, v11
	s_nop 1
	v_cndmask_b32_e32 v13, v39, v13, vcc
	v_lshlrev_b32_e32 v13, 2, v13
	s_nop 1
	v_add_f32_dpp v10, v10, v10 quad_perm:[1,0,3,2] row_mask:0xf bank_mask:0xf
	v_xor_b32_e32 v15, 2, v39
	v_cmp_lt_i32_e32 vcc, v15, v11
	s_nop 1
	v_cndmask_b32_e32 v15, v39, v15, vcc
	v_lshlrev_b32_e32 v15, 2, v15
	s_nop 1
	v_add_f32_dpp v10, v10, v10 quad_perm:[2,3,0,1] row_mask:0xf bank_mask:0xf
	v_xor_b32_e32 v22, 4, v39
	v_cmp_lt_i32_e32 vcc, v22, v11
	s_nop 1
	v_cndmask_b32_e32 v22, v39, v22, vcc
	v_lshlrev_b32_e32 v41, 2, v22
	s_nop 1
	v_add_f32_dpp v10, v10, v10 row_half_mirror row_mask:0xf bank_mask:0xf
	v_xor_b32_e32 v22, 8, v39
	v_cmp_lt_i32_e32 vcc, v22, v11
	s_nop 1
	v_cndmask_b32_e32 v22, v39, v22, vcc
	v_lshlrev_b32_e32 v43, 2, v22
	s_nop 1
	v_add_f32_dpp v10, v10, v10 row_mirror row_mask:0xf bank_mask:0xf
	v_xor_b32_e32 v22, 16, v39
	v_cmp_lt_i32_e32 vcc, v22, v11
	s_nop 1
	v_cndmask_b32_e32 v22, v39, v22, vcc
	v_lshlrev_b32_e32 v67, 2, v22
	ds_bpermute_b32 v22, v67, v10
	s_waitcnt lgkmcnt(0)
	v_add_f32_e32 v10, v10, v22
	v_xor_b32_e32 v22, 32, v39
	v_cmp_lt_i32_e32 vcc, v22, v11
	s_nop 1
	v_cndmask_b32_e32 v11, v39, v22, vcc
	v_lshlrev_b32_e32 v69, 2, v11
	ds_bpermute_b32 v11, v69, v10
	s_waitcnt lgkmcnt(0)
	v_add_f32_e32 v71, v10, v11
	v_fmac_f32_e32 v25, 0xba000000, v71
	v_fmac_f32_e32 v24, 0xba000000, v71
	v_fmac_f32_e32 v27, 0xba000000, v71
	v_fmac_f32_e32 v109, 0xba000000, v71
	v_fmac_f32_e32 v26, 0xba000000, v71
	v_fmac_f32_e32 v108, 0xba000000, v71
	v_mov_b32_e32 v22, v25
	v_mov_b32_e32 v23, v24
	v_fmac_f32_e32 v107, 0xba000000, v71
	v_fmac_f32_e32 v106, 0xba000000, v71
	v_mov_b32_e32 v10, v109
	v_mov_b32_e32 v11, v108
	v_pk_mul_f32 v[22:23], v[22:23], v[22:23]
	v_mov_b32_e32 v28, v27
	v_mov_b32_e32 v29, v26
	v_pk_fma_f32 v[10:11], v[10:11], v[10:11], v[22:23]
	v_mov_b32_e32 v22, v107
	v_mov_b32_e32 v23, v106
	v_pk_mul_f32 v[28:29], v[28:29], v[28:29]
	v_fmac_f32_e32 v21, 0xba000000, v71
	v_pk_fma_f32 v[22:23], v[22:23], v[22:23], v[28:29]
	v_fmac_f32_e32 v111, 0xba000000, v71
	v_fmac_f32_e32 v110, 0xba000000, v71
	v_fmac_f32_e32 v20, 0xba000000, v71
	v_pk_add_f32 v[10:11], v[10:11], v[22:23]
	v_mov_b32_e32 v22, v111
	v_mov_b32_e32 v23, v21
	v_mov_b32_e32 v28, v20
	v_mov_b32_e32 v29, v110
	v_pk_add_f32 v[10:11], v[10:11], v[10:11] op_sel_hi:[0,1]
	v_pk_mul_f32 v[22:23], v[22:23], v[22:23]
	v_pk_mul_f32 v[28:29], v[28:29], v[28:29]
	v_fmac_f32_e32 v16, 0xba000000, v71
	v_pk_mov_b32 v[30:31], v[28:29], v[22:23] op_sel:[1,0]
	v_mov_b32_e32 v29, v23
	v_fmac_f32_e32 v18, 0xba000000, v71
	v_fmac_f32_e32 v17, 0xba000000, v71
	v_mul_f32_e32 v10, v16, v16
	v_pk_add_f32 v[22:23], v[30:31], v[28:29]
	v_fmac_f32_e32 v19, 0xba000000, v71
	v_pk_fma_f32 v[28:29], v[16:17], v[16:17], v[10:11] op_sel_hi:[1,1,0]
	v_mul_f32_e32 v10, v18, v18
	v_pk_add_f32 v[22:23], v[22:23], v[22:23] op_sel_hi:[0,1]
	v_pk_fma_f32 v[30:31], v[18:19], v[18:19], v[10:11] op_sel_hi:[1,1,0]
	v_fmac_f32_e32 v102, 0xba000000, v71
	v_fmac_f32_e32 v14, 0xba000000, v71
	v_fmac_f32_e32 v104, 0xba000000, v71
	v_fmac_f32_e32 v12, 0xba000000, v71
	v_mul_f32_e32 v28, v12, v12
	v_mul_f32_e32 v30, v104, v104
	v_mul_f32_e32 v22, v14, v14
	v_mul_f32_e32 v10, v102, v102
	v_pk_add_f32 v[28:29], v[28:29], v[30:31]
	v_pk_add_f32 v[10:11], v[22:23], v[10:11]
	v_fmac_f32_e32 v9, 0xba000000, v71
	v_pk_add_f32 v[10:11], v[28:29], v[10:11]
	global_load_dwordx4 v[28:31], v[44:45], off
	global_load_dwordx4 v[118:121], v[46:47], off
	global_load_dwordx4 v[128:131], v[44:45], off offset:1024
	global_load_dwordx4 v[132:135], v[46:47], off offset:1024
	global_load_dwordx4 v[136:139], v[44:45], off offset:2048
	global_load_dwordx4 v[140:143], v[46:47], off offset:2048
	global_load_dwordx4 v[144:147], v[44:45], off offset:3072
	global_load_dwordx4 v[148:151], v[46:47], off offset:3072
	global_load_dwordx4 v[152:155], v[48:49], off
	global_load_dwordx4 v[156:159], v[50:51], off
	global_load_dwordx4 v[160:163], v[52:53], off
	global_load_dwordx4 v[168:171], v[54:55], off
	global_load_dwordx4 v[172:175], v[56:57], off
	global_load_dwordx4 v[176:179], v[58:59], off
	global_load_dwordx4 v[180:183], v[60:61], off
	global_load_dwordx4 v[184:187], v[62:63], off
	v_fmac_f32_e32 v101, 0xba000000, v71
	v_fmac_f32_e32 v100, 0xba000000, v71
	v_fmac_f32_e32 v8, 0xba000000, v71
	v_mov_b32_e32 v22, v101
	v_mov_b32_e32 v23, v9
	v_mov_b32_e32 v112, v8
	v_mov_b32_e32 v113, v100
	v_fmac_f32_e32 v4, 0xba000000, v71
	v_pk_mul_f32 v[22:23], v[22:23], v[22:23]
	v_pk_mul_f32 v[112:113], v[112:113], v[112:113]
	v_fmamk_f32 v116, v71, 0xba000000, v6
	v_fmamk_f32 v5, v71, 0xba000000, v5
	v_mul_f32_e32 v6, v4, v4
	v_pk_mov_b32 v[114:115], v[112:113], v[22:23] op_sel:[1,0]
	v_mov_b32_e32 v113, v23
	v_fmamk_f32 v117, v71, 0xba000000, v7
	v_pk_fma_f32 v[6:7], v[4:5], v[4:5], v[6:7] op_sel_hi:[1,1,0]
	v_pk_add_f32 v[22:23], v[114:115], v[112:113]
	v_mul_f32_e32 v6, v116, v116
	v_pk_add_f32 v[10:11], v[10:11], v[10:11] op_sel_hi:[0,1]
	v_pk_add_f32 v[22:23], v[22:23], v[22:23] op_sel_hi:[0,1]
	v_pk_fma_f32 v[114:115], v[116:117], v[116:117], v[6:7] op_sel_hi:[1,1,0]
	v_fmamk_f32 v113, v71, 0xba000000, v3
	v_fmamk_f32 v112, v71, 0xba000000, v2
	v_fmamk_f32 v1, v71, 0xba000000, v1
	v_fmac_f32_e32 v0, 0xba000000, v71
	v_mul_f32_e32 v6, v0, v0
	v_mul_f32_e32 v114, v1, v1
	v_mul_f32_e32 v22, v112, v112
	v_mul_f32_e32 v10, v113, v113
	v_pk_add_f32 v[2:3], v[6:7], v[114:115]
	v_pk_add_f32 v[6:7], v[22:23], v[10:11]
	s_nop 0
	v_pk_add_f32 v[2:3], v[2:3], v[6:7]
	v_mov_b32_e32 v7, v27
	v_add_f32_e32 v2, v2, v3
	s_nop 1
	v_add_f32_dpp v2, v2, v2 quad_perm:[1,0,3,2] row_mask:0xf bank_mask:0xf
	s_nop 1
	v_add_f32_dpp v2, v2, v2 quad_perm:[2,3,0,1] row_mask:0xf bank_mask:0xf
	s_nop 1
	v_add_f32_dpp v2, v2, v2 row_half_mirror row_mask:0xf bank_mask:0xf
	s_nop 1
	v_add_f32_dpp v2, v2, v2 row_mirror row_mask:0xf bank_mask:0xf
	ds_bpermute_b32 v3, v67, v2
	s_waitcnt lgkmcnt(0)
	v_add_f32_e32 v3, v2, v3
	ds_bpermute_b32 v6, v69, v3
	v_mov_b32_e32 v2, v109
	s_waitcnt lgkmcnt(0)
	v_add_f32_e32 v3, v3, v6
	v_fmamk_f32 v3, v3, 0x3a000000, v37
	v_mul_f32_e32 v6, 0x4b800000, v3
	v_cmp_gt_f32_e32 vcc, s28, v3
	s_nop 1
	v_cndmask_b32_e32 v3, v3, v6, vcc
	v_rsq_f32_e32 v10, v3
	v_mov_b32_e32 v3, v25
	v_mov_b32_e32 v6, v107
	v_mul_f32_e32 v11, 0x45800000, v10
	v_cndmask_b32_e32 v114, v10, v11, vcc
	v_pk_mul_f32 v[2:3], v[2:3], v[114:115] op_sel_hi:[1,0]
	v_pk_mul_f32 v[6:7], v[6:7], v[114:115] op_sel_hi:[1,0]
	v_cmp_lt_i32_e32 vcc, s27, v96
	s_waitcnt vmcnt(14)
	v_pk_fma_f32 v[30:31], v[30:31], v[6:7], v[120:121]
	v_pk_fma_f32 v[28:29], v[28:29], v[2:3], v[118:119]
	s_and_saveexec_b64 s[24:25], vcc
	s_cbranch_execz .LBB0_1580
	v_mov_b32_e32 v95, v35
	v_lshl_add_u64 v[2:3], v[98:99], 0, v[94:95]
	global_store_dwordx4 v[2:3], v[28:31], off

.LBB0_1822:
	s_or_b64 exec, exec, s[24:25]
	v_pk_add_f32 v[10:11], v[72:73], v[24:25]
	v_pk_add_f32 v[22:23], v[70:71], v[26:27]
	s_waitcnt vmcnt(2)
	v_add_f32_e32 v13, v16, v17
	v_pk_add_f32 v[10:11], v[10:11], v[22:23]
	v_add_f32_e32 v69, v18, v19
	v_add_f32_e32 v11, 0, v11
	v_add_f32_e32 v67, v10, v11
	v_pk_add_f32 v[10:11], v[76:77], v[20:21]
	v_pk_add_f32 v[22:23], v[12:13], v[68:69]
	v_pk_add_f32 v[10:11], v[10:11], v[10:11] op_sel_hi:[0,1]
	v_mov_b32_e32 v15, v11
	v_pk_add_f32 v[10:11], v[14:15], v[66:67]
	s_waitcnt vmcnt(1)
	v_add_f32_e32 v79, v0, v1
	v_pk_add_f32 v[10:11], v[22:23], v[10:11]
	v_pk_add_f32 v[22:23], v[74:75], v[8:9]
	v_pk_add_f32 v[10:11], v[10:11], v[10:11] op_sel_hi:[0,1]
	v_pk_add_f32 v[22:23], v[22:23], v[22:23] op_sel_hi:[0,1]
	v_add_f32_e32 v81, v2, v3
	s_waitcnt vmcnt(0)
	v_mov_b32_e32 v78, v4
	v_mov_b32_e32 v80, v5
	v_mov_b32_e32 v22, v6
	v_mov_b32_e32 v10, v7
	v_pk_add_f32 v[78:79], v[78:79], v[80:81]
	v_pk_add_f32 v[10:11], v[22:23], v[10:11]
	v_xor_b32_e32 v13, 1, v92
	v_pk_add_f32 v[10:11], v[78:79], v[10:11]
	v_mov_b32_e32 v61, v29
	v_add_f32_e32 v10, v10, v11
	v_and_b32_e32 v11, 64, v92
	v_add_u32_e32 v11, 64, v11
	v_cmp_lt_i32_e32 vcc, v13, v11
	v_mov_b32_e32 v63, v29
	s_nop 0
	v_cndmask_b32_e32 v13, v92, v13, vcc
	v_lshlrev_b32_e32 v13, 2, v13
	s_nop 1
	v_add_f32_dpp v10, v10, v10 quad_perm:[1,0,3,2] row_mask:0xf bank_mask:0xf
	v_xor_b32_e32 v15, 2, v92
	v_cmp_lt_i32_e32 vcc, v15, v11
	s_nop 1
	v_cndmask_b32_e32 v15, v92, v15, vcc
	v_lshlrev_b32_e32 v15, 2, v15
	s_nop 1
	v_add_f32_dpp v10, v10, v10 quad_perm:[2,3,0,1] row_mask:0xf bank_mask:0xf
	v_xor_b32_e32 v22, 4, v92
	v_cmp_lt_i32_e32 vcc, v22, v11
	s_nop 1
	v_cndmask_b32_e32 v22, v92, v22, vcc
	v_lshlrev_b32_e32 v51, 2, v22
	s_nop 1
	v_add_f32_dpp v10, v10, v10 row_half_mirror row_mask:0xf bank_mask:0xf
	v_xor_b32_e32 v22, 8, v92
	v_cmp_lt_i32_e32 vcc, v22, v11
	s_nop 1
	v_cndmask_b32_e32 v22, v92, v22, vcc
	v_lshlrev_b32_e32 v53, 2, v22
	s_nop 1
	v_add_f32_dpp v10, v10, v10 row_mirror row_mask:0xf bank_mask:0xf
	v_xor_b32_e32 v22, 16, v92
	v_cmp_lt_i32_e32 vcc, v22, v11
	s_nop 1
	v_cndmask_b32_e32 v22, v92, v22, vcc
	v_lshlrev_b32_e32 v55, 2, v22
	ds_bpermute_b32 v22, v55, v10
	s_waitcnt lgkmcnt(0)
	v_add_f32_e32 v10, v10, v22
	v_xor_b32_e32 v22, 32, v92
	v_cmp_lt_i32_e32 vcc, v22, v11
	s_nop 1
	v_cndmask_b32_e32 v11, v92, v22, vcc
	v_lshlrev_b32_e32 v57, 2, v11
	ds_bpermute_b32 v11, v57, v10
	s_waitcnt lgkmcnt(0)
	v_add_f32_e32 v59, v10, v11
	v_fmac_f32_e32 v25, 0xba000000, v59
	v_fmac_f32_e32 v24, 0xba000000, v59
	v_fmac_f32_e32 v27, 0xba000000, v59
	v_fmac_f32_e32 v73, 0xba000000, v59
	v_fmac_f32_e32 v26, 0xba000000, v59
	v_fmac_f32_e32 v72, 0xba000000, v59
	v_mov_b32_e32 v22, v25
	v_mov_b32_e32 v23, v24
	v_fmac_f32_e32 v71, 0xba000000, v59
	v_fmac_f32_e32 v70, 0xba000000, v59
	v_mov_b32_e32 v10, v73
	v_mov_b32_e32 v11, v72
	v_pk_mul_f32 v[22:23], v[22:23], v[22:23]
	v_mov_b32_e32 v78, v27
	v_mov_b32_e32 v79, v26
	v_pk_fma_f32 v[10:11], v[10:11], v[10:11], v[22:23]
	v_mov_b32_e32 v22, v71
	v_mov_b32_e32 v23, v70
	v_pk_mul_f32 v[78:79], v[78:79], v[78:79]
	v_fmac_f32_e32 v76, 0xba000000, v59
	v_pk_fma_f32 v[22:23], v[22:23], v[22:23], v[78:79]
	v_fmac_f32_e32 v21, 0xba000000, v59
	v_fmac_f32_e32 v77, 0xba000000, v59
	v_pk_add_f32 v[10:11], v[10:11], v[22:23]
	v_fmac_f32_e32 v20, 0xba000000, v59
	v_mov_b32_e32 v84, v77
	v_mov_b32_e32 v85, v21
	v_mov_b32_e32 v21, v76
	v_pk_add_f32 v[10:11], v[10:11], v[10:11] op_sel_hi:[0,1]
	v_pk_mul_f32 v[22:23], v[84:85], v[84:85]
	v_pk_mul_f32 v[76:77], v[20:21], v[20:21]
	v_fmac_f32_e32 v16, 0xba000000, v59
	v_pk_mov_b32 v[78:79], v[76:77], v[22:23] op_sel:[1,0]
	v_mov_b32_e32 v77, v23
	v_fmac_f32_e32 v17, 0xba000000, v59
	v_fmac_f32_e32 v18, 0xba000000, v59
	v_mul_f32_e32 v10, v16, v16
	v_pk_add_f32 v[22:23], v[78:79], v[76:77]
	v_fmac_f32_e32 v19, 0xba000000, v59
	v_pk_fma_f32 v[76:77], v[16:17], v[16:17], v[10:11] op_sel_hi:[1,1,0]
	v_mul_f32_e32 v10, v18, v18
	v_pk_add_f32 v[22:23], v[22:23], v[22:23] op_sel_hi:[0,1]
	v_pk_fma_f32 v[78:79], v[18:19], v[18:19], v[10:11] op_sel_hi:[1,1,0]
	v_fmac_f32_e32 v66, 0xba000000, v59
	v_fmac_f32_e32 v14, 0xba000000, v59
	v_fmac_f32_e32 v68, 0xba000000, v59
	v_fmac_f32_e32 v12, 0xba000000, v59
	v_mul_f32_e32 v76, v12, v12
	v_mul_f32_e32 v78, v68, v68
	v_mul_f32_e32 v22, v14, v14
	v_mul_f32_e32 v10, v66, v66
	v_pk_add_f32 v[76:77], v[76:77], v[78:79]
	v_pk_add_f32 v[10:11], v[22:23], v[10:11]
	v_fmac_f32_e32 v74, 0xba000000, v59
	v_pk_add_f32 v[10:11], v[76:77], v[10:11]
	global_load_dwordx4 v[76:79], v[30:31], off
	global_load_dwordx4 v[80:83], v[32:33], off
	global_load_dwordx4 v[96:99], v[30:31], off offset:1024
	global_load_dwordx4 v[100:103], v[32:33], off offset:1024
	global_load_dwordx4 v[104:107], v[30:31], off offset:2048
	global_load_dwordx4 v[108:111], v[32:33], off offset:2048
	global_load_dwordx4 v[112:115], v[30:31], off offset:3072
	global_load_dwordx4 v[116:119], v[32:33], off offset:3072
	global_load_dwordx4 v[120:123], v[34:35], off
	global_load_dwordx4 v[124:127], v[36:37], off
	global_load_dwordx4 v[128:131], v[38:39], off
	global_load_dwordx4 v[132:135], v[40:41], off
	global_load_dwordx4 v[136:139], v[42:43], off
	global_load_dwordx4 v[140:143], v[44:45], off
	global_load_dwordx4 v[144:147], v[46:47], off
	global_load_dwordx4 v[148:151], v[48:49], off
	v_fmac_f32_e32 v9, 0xba000000, v59
	v_fmac_f32_e32 v75, 0xba000000, v59
	v_fmac_f32_e32 v8, 0xba000000, v59
	v_mov_b32_e32 v86, v75
	v_mov_b32_e32 v87, v9
	v_mov_b32_e32 v9, v74
	v_pk_add_f32 v[10:11], v[10:11], v[10:11] op_sel_hi:[0,1]
	v_pk_mul_f32 v[22:23], v[86:87], v[86:87]
	v_pk_mul_f32 v[74:75], v[8:9], v[8:9]
	v_fmamk_f32 v0, v59, 0xba000000, v0
	v_pk_mov_b32 v[88:89], v[74:75], v[22:23] op_sel:[1,0]
	v_mov_b32_e32 v75, v23
	v_fmamk_f32 v1, v59, 0xba000000, v1
	v_fmac_f32_e32 v2, 0xba000000, v59
	v_mul_f32_e32 v10, v0, v0
	v_pk_add_f32 v[22:23], v[88:89], v[74:75]
	v_fmamk_f32 v3, v59, 0xba000000, v3
	v_pk_fma_f32 v[74:75], v[0:1], v[0:1], v[10:11] op_sel_hi:[1,1,0]
	v_mul_f32_e32 v10, v2, v2
	v_pk_add_f32 v[22:23], v[22:23], v[22:23] op_sel_hi:[0,1]
	v_pk_fma_f32 v[88:89], v[2:3], v[2:3], v[10:11] op_sel_hi:[1,1,0]
	v_fmamk_f32 v95, v59, 0xba000000, v7
	v_fmamk_f32 v94, v59, 0xba000000, v6
	v_fmamk_f32 v5, v59, 0xba000000, v5
	v_fmac_f32_e32 v4, 0xba000000, v59
	v_mul_f32_e32 v74, v4, v4
	v_mul_f32_e32 v88, v5, v5
	v_mul_f32_e32 v22, v94, v94
	v_mul_f32_e32 v10, v95, v95
	v_pk_add_f32 v[6:7], v[74:75], v[88:89]
	v_pk_add_f32 v[10:11], v[22:23], v[10:11]
	v_mov_b32_e32 v59, v29
	v_pk_add_f32 v[6:7], v[6:7], v[10:11]
	v_mov_b32_e32 v11, v27
	v_add_f32_e32 v6, v6, v7
	s_nop 1
	v_add_f32_dpp v6, v6, v6 quad_perm:[1,0,3,2] row_mask:0xf bank_mask:0xf
	s_nop 1
	v_add_f32_dpp v6, v6, v6 quad_perm:[2,3,0,1] row_mask:0xf bank_mask:0xf
	s_nop 1
	v_add_f32_dpp v6, v6, v6 row_half_mirror row_mask:0xf bank_mask:0xf
	s_nop 1
	v_add_f32_dpp v6, v6, v6 row_mirror row_mask:0xf bank_mask:0xf
	ds_bpermute_b32 v7, v55, v6
	s_waitcnt lgkmcnt(0)
	v_add_f32_e32 v7, v6, v7
	ds_bpermute_b32 v10, v57, v7
	v_mov_b32_e32 v6, v73
	v_mov_b32_e32 v73, v24
	v_mov_b32_e32 v57, v29
	s_waitcnt lgkmcnt(0)
	v_add_f32_e32 v7, v7, v10
	v_fmamk_f32 v7, v7, 0x3a000000, v91
	v_mul_f32_e32 v10, 0x4b800000, v7
	v_cmp_gt_f32_e32 vcc, s29, v7
	s_nop 1
	v_cndmask_b32_e32 v7, v7, v10, vcc
	v_rsq_f32_e32 v13, v7
	v_mov_b32_e32 v7, v25
	v_mov_b32_e32 v10, v71
	v_mov_b32_e32 v71, v26
	v_mul_f32_e32 v15, 0x45800000, v13
	v_cndmask_b32_e32 v88, v13, v15, vcc
	v_pk_mul_f32 v[6:7], v[6:7], v[88:89] op_sel_hi:[1,0]
	v_pk_mul_f32 v[10:11], v[10:11], v[88:89] op_sel_hi:[1,0]
	s_waitcnt vmcnt(14)
	v_pk_fma_f32 v[76:77], v[76:77], v[6:7], v[80:81]
	v_pk_fma_f32 v[78:79], v[78:79], v[10:11], v[82:83]
	v_lshl_add_u64 v[6:7], v[64:65], 0, v[28:29]
	global_store_dwordx4 v[6:7], v[76:79], off
	v_pk_mul_f32 v[10:11], v[70:71], v[88:89] op_sel_hi:[1,0]
	v_pk_mul_f32 v[22:23], v[72:73], v[88:89] op_sel_hi:[1,0]
	v_pk_mul_f32 v[20:21], v[20:21], v[88:89] op_sel_hi:[1,0]
	v_pk_mul_f32 v[16:17], v[16:17], v[88:89] op_sel_hi:[1,0]
	v_mov_b32_e32 v15, v66
	v_mov_b32_e32 v13, v68
	v_pk_mul_f32 v[14:15], v[14:15], v[88:89] op_sel_hi:[1,0]
	v_pk_mul_f32 v[2:3], v[2:3], v[88:89] op_sel_hi:[1,0]
	v_pk_mul_f32 v[0:1], v[0:1], v[88:89] op_sel_hi:[1,0]
	v_pk_mul_f32 v[4:5], v[4:5], v[88:89] op_sel_hi:[1,0]
	s_waitcnt vmcnt(13)
	v_pk_fma_f32 v[22:23], v[96:97], v[22:23], v[100:101]
	v_pk_fma_f32 v[24:25], v[98:99], v[10:11], v[102:103]
	global_store_dwordx4 v[6:7], v[22:25], off offset:1024
	v_pk_mul_f32 v[10:11], v[84:85], v[88:89] op_sel_hi:[1,0]
	s_waitcnt vmcnt(12)
	v_pk_fma_f32 v[20:21], v[104:105], v[20:21], v[108:109]
	v_pk_fma_f32 v[22:23], v[106:107], v[10:11], v[110:111]
	global_store_dwordx4 v[6:7], v[20:23], off offset:2048
	v_pk_mul_f32 v[10:11], v[18:19], v[88:89] op_sel_hi:[1,0]
	s_waitcnt vmcnt(11)
	v_pk_fma_f32 v[16:17], v[112:113], v[16:17], v[116:117]
	v_pk_fma_f32 v[18:19], v[114:115], v[10:11], v[118:119]
	global_store_dwordx4 v[6:7], v[16:19], off offset:3072
	v_pk_mul_f32 v[10:11], v[12:13], v[88:89] op_sel_hi:[1,0]
	v_lshl_add_u64 v[6:7], v[64:65], 0, v[56:57]
	s_waitcnt vmcnt(10)
	v_pk_fma_f32 v[10:11], v[120:121], v[10:11], v[124:125]
	v_pk_fma_f32 v[12:13], v[122:123], v[14:15], v[126:127]
	global_store_dwordx4 v[6:7], v[10:13], off
	s_nop 1
	v_pk_mul_f32 v[20:21], v[86:87], v[88:89] op_sel_hi:[1,0]
	v_pk_mul_f32 v[6:7], v[8:9], v[88:89] op_sel_hi:[1,0]
	v_lshl_add_u64 v[18:19], v[64:65], 0, v[58:59]
	s_waitcnt vmcnt(9)
	v_pk_fma_f32 v[6:7], v[128:129], v[6:7], v[132:133]
	v_pk_fma_f32 v[8:9], v[130:131], v[20:21], v[134:135]
	global_store_dwordx4 v[18:19], v[6:9], off
	v_lshl_add_u64 v[14:15], v[64:65], 0, v[60:61]
	s_waitcnt vmcnt(8)
	v_pk_fma_f32 v[0:1], v[136:137], v[0:1], v[140:141]
	v_pk_fma_f32 v[2:3], v[138:139], v[2:3], v[142:143]
	global_store_dwordx4 v[14:15], v[0:3], off
	v_pk_mul_f32 v[10:11], v[94:95], v[88:89] op_sel_hi:[1,0]
	s_waitcnt vmcnt(7)
	v_pk_fma_f32 v[152:153], v[144:145], v[4:5], v[148:149]
	v_pk_fma_f32 v[154:155], v[146:147], v[10:11], v[150:151]
	v_lshl_add_u64 v[4:5], v[64:65], 0, v[62:63]
	global_store_dwordx4 v[4:5], v[152:155], off
